# attention fast loop copy 2 (small units) also gets the SrcC fold (live registers of the -m_ref block parked around the loop)
# speedup vs baseline: 1.0095x; 1.0007x over previous
; __device__ __forceinline__ int swz(int row) { return ((row & 3) << 2) | ((row >> 2) & 3); }
; __device__ __forceinline__ void dma_tile(const bf16* kbase, const bf16* vbase, int key0, ldsp stage, int wave, int lane) {
;     ...
;     for (int j = 0; j < 2; ++j) { const int rowb = 8 * wave + 4 * j, row = rowb + (lane >> 4), cc = (lane & 15) ^ swz(row); const size_t off = (size_t)(key0 + row) * 128 + cc * 8;
;         glds16(kbase + off, sb + rowb * 256);
;         glds16(vbase + off, sb + RKV + rowb * 256); }
; __device__ __forceinline__ void diff_unit(const bf16* proj, bf16* og0, const float* nwv, float lam_full, float one_m_li, int h, int qb, ldsp lds, int tid, int lane, int wave, int mode) {
;     ...
;     for (int i = 2; i < nt; ++i) {
;         asm volatile("s_waitcnt vmcnt(8)" ::: "memory");
;         __builtin_amdgcn_s_barrier();
;         asm volatile("" ::: "memory");
;         { int n = i + 3; n = n < nt ? n : nt - 1; dma_tile(kbase, vbase, 64 * (n - 2), lds + ((i + 3) & 3) * RSTG, wave, lane); }
;         ldsp Ks = lds + (i & 3) * RSTG, Vs = Ks + RKV;
;         flash_fast_tile2<4>(Ks, Vs, M, qf, o, mc, l);
.LBB0_456:
	s_andn2_b64 vcc, exec, s[28:29]
	s_cbranch_vccnz .LBB0_465
	s_mov_b32 s6, 2
	s_cmp_lt_i32 5, s59
	s_cselect_b32 s1, 5, s60
	v_lshl_add_u32 v160, s1, 6, v183
	v_add_u32_e32 v161, s35, v160
	v_add_u32_e32 v160, s31, v160
	v_lshlrev_b32_e32 v161, 8, v161
	v_lshlrev_b32_e32 v160, 8, v160
	v_lshl_add_u32 v161, v156, 1, v161
	v_lshl_add_u32 v160, v154, 1, v160
	s_and_b64 vcc, exec, s[20:21]
	s_cbranch_vccnz .Lap_skip2
	s_setprio 1
.Lap_skip2:
	v_mov_b32_e32 v162, v214
	v_mov_b32_e32 v163, v216
	v_mov_b32_e32 v164, v218
	v_mov_b32_e32 v166, v220
	v_mov_b32_e32 v168, v222
	v_mov_b32_e32 v170, v224
	v_mov_b32_e32 v172, v226
	v_mov_b32_e32 v174, v228
	v_sub_f32_e32 v214, 0, v207
	v_sub_f32_e32 v215, 0, v207
	v_sub_f32_e32 v216, 0, v207
	v_sub_f32_e32 v217, 0, v207
	v_sub_f32_e32 v218, 0, v207
	v_sub_f32_e32 v219, 0, v207
	v_sub_f32_e32 v220, 0, v207
	v_sub_f32_e32 v221, 0, v207
	v_sub_f32_e32 v222, 0, v207
	v_sub_f32_e32 v223, 0, v207
	v_sub_f32_e32 v224, 0, v207
	v_sub_f32_e32 v225, 0, v207
	v_sub_f32_e32 v226, 0, v207
	v_sub_f32_e32 v227, 0, v207
	v_sub_f32_e32 v228, 0, v207
	v_sub_f32_e32 v229, 0, v207
	s_branch .LBB0_459

; #define LAS __attribute__((address_space(3)))
; template <int KS>
; __device__ __forceinline__ void flash_fast_tile2(ldsp Ks, ldsp Vs, const FragMap<KS>& M, const bf16x8 (&qf)[KS], f32x16 (&o)[4], float& mc, float& l) {
;     bf16x8 kf[KS];
; #pragma unroll
;     for (int ks = 0; ks < KS; ++ks) kf[ks] = *(LAS const bf16x8*)(Ks + M.k[ks]);
; #pragma unroll 1
;     for (int h = 0; h < 2; ++h) {
;         ldsp Vh = Vs + h * 32 * 256;
;         s16x4 vl[8], vh[8];
; #pragma unroll
;         for (int b = 0; b < 4; ++b) { vl[2 * b] = vtr(Vh + M.v[0][b]); vh[2 * b] = vtr(Vh + M.v[1][b]); vl[2 * b + 1] = vtr(Vh + 16 * 256 + M.v[0][b]); vh[2 * b + 1] = vtr(Vh + 16 * 256 + M.v[1][b]); }
;         f32x16 s0;
; #pragma unroll
;         for (int r = 0; r < 16; ++r) s0[r] = 0.f;
; #pragma unroll
;         for (int ks = 0; ks < KS; ++ks) s0 = MFMA32(kf[ks], qf[ks], s0);
;         if (h == 0) {
; #pragma unroll
;             for (int ks = 0; ks < KS; ++ks) kf[ks] = *(LAS const bf16x8*)(Ks + 32 * 256 + M.k[ks]); }
;         float m0 = fmaxf(s0[0], s0[1]), m1 = fmaxf(s0[2], s0[3]);
; #pragma unroll
;         for (int r = 4; r < 16; r += 4) { m0 = fmaxf(fmaxf(m0, s0[r]), s0[r + 1]); m1 = fmaxf(fmaxf(m1, s0[r + 2]), s0[r + 3]); }
;         const float mx = xmax32(fmaxf(m0, m1));
;         if (!__all(mx - mc <= 6.f)) {
;             const float mnew = fmaxf(mc, mx), alpha = __builtin_amdgcn_exp2f(mc - mnew);
;             mc = mnew; l *= alpha;
; #pragma unroll
;             for (int b = 0; b < 4; ++b) o[b] *= alpha;
;         }
;         float ps0 = 0.f, ps1 = 0.f;
; #pragma unroll
;         for (int r = 0; r < 16; r += 2) { s0[r] = __builtin_amdgcn_exp2f(s0[r] - mc); s0[r + 1] = __builtin_amdgcn_exp2f(s0[r + 1] - mc); ps0 += s0[r]; ps1 += s0[r + 1]; }
;         l += ps0 + ps1;
;         const bf16x8 p0 = pack8<0>(s0), p1 = pack8<1>(s0);
; #pragma unroll
;         for (int b = 0; b < 4; ++b) {
;             o[b] = MFMA32(cat8(vl[2 * b], vh[2 * b]), p0, o[b]);
;             o[b] = MFMA32(cat8(vl[2 * b + 1], vh[2 * b + 1]), p1, o[b]); }
; __device__ __forceinline__ void diff_unit(const bf16* proj, bf16* og0, const float* nwv, float lam_full, float one_m_li, int h, int qb, ldsp lds, int tid, int lane, int wave, int mode) {
;     ...
;         { int n = i + 3; n = n < nt ? n : nt - 1; dma_tile(kbase, vbase, 64 * (n - 2), lds + ((i + 3) & 3) * RSTG, wave, lane); }
.LBB0_459:
	s_add_i32 s0, s6, 3
	s_lshl_b32 s0, s0, 15
	s_and_b32 s0, s0, 0x18000
	s_waitcnt vmcnt(8)
	s_barrier
	s_add_i32 s1, s0, 0x4000
	s_add_i32 m0, s34, s0
	s_add_i32 s4, s6, 4
	global_load_lds_dwordx4 v160, s[24:25]
	s_add_i32 m0, s1, s34
	s_nop 0
	global_load_lds_dwordx4 v160, s[26:27]
	s_add_i32 m0, s36, s0
	s_nop 0
	global_load_lds_dwordx4 v161, s[24:25]
	s_add_i32 m0, s1, s36
	s_cmp_lt_i32 s4, s59
	global_load_lds_dwordx4 v161, s[26:27]
	s_cselect_b32 s4, 0x4000, 0
	v_add_u32_e32 v160, s4, v160
	v_add_u32_e32 v161, s4, v161
	s_lshl_b32 s0, s6, 15
	s_and_b32 s0, s0, 0x18000
	s_add_i32 s7, s0, 0
	v_add_u32_e32 v0, s7, v165
	v_add_u32_e32 v15, s7, v169
	v_add_u32_e32 v14, s7, v167
	ds_read_b128 v[2:5], v0
	ds_read_b128 v[6:9], v14
	v_add_u32_e32 v209, s7, v171
	ds_read_b128 v[10:13], v15
	ds_read_b128 v[112:115], v209
	s_mov_b32 s28, 0
	s_mov_b64 s[0:1], -1
	s_branch .LBB0_461
.LBB0_460:
	v_exp_f32_e32 v80, v80
	v_exp_f32_e32 v81, v81
	v_exp_f32_e32 v82, v82
	v_exp_f32_e32 v83, v83
	v_exp_f32_e32 v84, v84
	v_exp_f32_e32 v85, v85
	v_exp_f32_e32 v86, v86
	v_exp_f32_e32 v87, v87
	v_add_f32_e32 v252, v80, v82
	v_add_f32_e32 v253, v81, v83
	v_cvt_pk_bf16_f32 v80, v80, v81
	v_cvt_pk_bf16_f32 v81, v82, v83
	v_cvt_pk_bf16_f32 v82, v84, v85
	v_cvt_pk_bf16_f32 v83, v86, v87
	v_exp_f32_e32 v88, v88
	v_exp_f32_e32 v89, v89
	v_mfma_f32_32x32x16_bf16 v[64:79], v[144:147], v[80:83], v[64:79]
	s_waitcnt lgkmcnt(10)
	v_mfma_f32_32x32x16_bf16 v[48:63], v[136:139], v[80:83], v[48:63]
	v_exp_f32_e32 v90, v90
	v_exp_f32_e32 v91, v91
	v_exp_f32_e32 v92, v92
	v_exp_f32_e32 v93, v93
	v_exp_f32_e32 v94, v94
	v_exp_f32_e32 v95, v95
	s_waitcnt lgkmcnt(6)
	v_mfma_f32_32x32x16_bf16 v[32:47], v[128:131], v[80:83], v[32:47]
	v_add_f32_e64 v252, v84, v252
	v_add_f32_e64 v253, v85, v253
	v_cvt_pk_bf16_f32 v84, v88, v89
	v_add_f32_e64 v252, v86, v252
	v_add_f32_e64 v253, v87, v253
	v_cvt_pk_bf16_f32 v85, v90, v91
	v_cvt_pk_bf16_f32 v86, v92, v93
	v_cvt_pk_bf16_f32 v87, v94, v95
	v_add_f32_e32 v252, v88, v252
	v_add_f32_e32 v253, v89, v253
	s_waitcnt lgkmcnt(2)
	v_mfma_f32_32x32x16_bf16 v[16:31], v[116:119], v[80:83], v[16:31]
	v_add_f32_e64 v252, v90, v252
	v_add_f32_e64 v253, v91, v253
	s_movk_i32 s28, 0x2000
	v_add_f32_e64 v252, v92, v252
	v_add_f32_e64 v253, v93, v253
	s_mov_b64 s[0:1], 0
	v_add_f32_e32 v252, v94, v252
	v_add_f32_e32 v253, v95, v253
	s_andn2_b64 vcc, exec, s[4:5]
	v_add_f32_e32 v211, v252, v253
	v_mfma_f32_32x32x16_bf16 v[64:79], v[140:143], v[84:87], v[64:79]
	v_add_f32_e32 v195, v195, v211
	v_mfma_f32_32x32x16_bf16 v[48:63], v[132:135], v[84:87], v[48:63]
	v_mfma_f32_32x32x16_bf16 v[32:47], v[124:127], v[84:87], v[32:47]
	s_waitcnt lgkmcnt(0)
	v_mfma_f32_32x32x16_bf16 v[16:31], v[120:123], v[84:87], v[16:31]
	s_cbranch_vccz .LBB0_458
.LBB0_461:
	s_xor_b64 s[4:5], s[0:1], -1
	s_add_i32 s0, s7, s28
	v_add_u32_e32 v80, s0, v173
	v_add_u32_e32 v81, s0, v189
	ds_read_b64_tr_b16 v[144:145], v80 offset:16384
	ds_read_b64_tr_b16 v[146:147], v81 offset:18432
	ds_read_b64_tr_b16 v[140:141], v80 offset:20480
	ds_read_b64_tr_b16 v[142:143], v81 offset:22528
	v_add_u32_e32 v80, s0, v175
	v_add_u32_e32 v81, s0, v248
	ds_read_b64_tr_b16 v[136:137], v80 offset:16384
	ds_read_b64_tr_b16 v[138:139], v81 offset:18432
	ds_read_b64_tr_b16 v[132:133], v80 offset:20480
	ds_read_b64_tr_b16 v[134:135], v81 offset:22528
	v_add_u32_e32 v80, s0, v177
	v_add_u32_e32 v81, s0, v249
	ds_read_b64_tr_b16 v[128:129], v80 offset:16384
	ds_read_b64_tr_b16 v[130:131], v81 offset:18432
	ds_read_b64_tr_b16 v[124:125], v80 offset:20480
	ds_read_b64_tr_b16 v[126:127], v81 offset:22528
	v_add_u32_e32 v80, s0, v179
	v_add_u32_e32 v81, s0, v250
	ds_read_b64_tr_b16 v[116:117], v80 offset:16384
	ds_read_b64_tr_b16 v[118:119], v81 offset:18432
	ds_read_b64_tr_b16 v[120:121], v80 offset:20480
	ds_read_b64_tr_b16 v[122:123], v81 offset:22528
	s_waitcnt lgkmcnt(14)
	v_mfma_f32_32x32x16_bf16 v[80:95], v[2:5], v[96:99], v[214:229]
	s_and_b64 vcc, exec, s[4:5]
	v_mfma_f32_32x32x16_bf16 v[80:95], v[6:9], v[100:103], v[80:95]
	v_mfma_f32_32x32x16_bf16 v[80:95], v[10:13], v[104:107], v[80:95]
	v_mfma_f32_32x32x16_bf16 v[80:95], v[112:115], v[108:111], v[80:95]
	s_cbranch_vccnz .LBB0_463
	ds_read_b128 v[2:5], v0 offset:8192
	ds_read_b128 v[6:9], v14 offset:8192
	ds_read_b128 v[10:13], v15 offset:8192
	ds_read_b128 v[112:115], v209 offset:8192
; __device__ __forceinline__ float xmax32(float v) { auto rr = __builtin_amdgcn_permlane32_swap(__float_as_uint(v), __float_as_uint(v), false, false); return fmaxf(__uint_as_float(rr[0]), __uint_as_float(rr[1])); }
; template <int KS>
; __device__ __forceinline__ void flash_fast_tile2(ldsp Ks, ldsp Vs, const FragMap<KS>& M, const bf16x8 (&qf)[KS], f32x16 (&o)[4], float& mc, float& l) {
;     ...
;         float m0 = fmaxf(s0[0], s0[1]), m1 = fmaxf(s0[2], s0[3]);
; #pragma unroll
;         for (int r = 4; r < 16; r += 4) { m0 = fmaxf(fmaxf(m0, s0[r]), s0[r + 1]); m1 = fmaxf(fmaxf(m1, s0[r + 2]), s0[r + 3]); }
;         const float mx = xmax32(fmaxf(m0, m1));
;         if (!__all(mx - mc <= 6.f)) {
;             const float mnew = fmaxf(mc, mx), alpha = __builtin_amdgcn_exp2f(mc - mnew);
;             mc = mnew; l *= alpha;
; #pragma unroll
;             for (int b = 0; b < 4; ++b) o[b] *= alpha;
;         }
.LBB0_463:
	s_nop 10
	v_max_f32_e32 v211, v82, v83
	v_max3_f32 v213, v80, v81, v84
	v_max3_f32 v211, v211, v86, v87
	v_max3_f32 v213, v213, v85, v88
	v_max3_f32 v211, v211, v90, v91
	v_max3_f32 v213, v213, v89, v92
	v_max3_f32 v211, v211, v94, v95
	v_max3_f32 v211, v213, v93, v211
	v_mov_b32_e32 v213, v211
	s_nop 1
	v_permlane32_swap_b32_e32 v211, v213
	v_max_f32_e32 v211, v211, v213
	v_cmp_ge_f32_e32 vcc, s53, v211
	s_cmp_eq_u64 vcc, exec
	s_cbranch_scc1 .LBB0_460
	v_max_f32_e32 v253, 0, v211
	v_sub_f32_e32 v252, 0, v253
	v_exp_f32_e32 v252, v252
	v_add_f32_e32 v207, v207, v253
	v_sub_f32_e32 v80, v80, v253
	v_sub_f32_e32 v81, v81, v253
	v_sub_f32_e32 v82, v82, v253
	v_sub_f32_e32 v83, v83, v253
	v_sub_f32_e32 v84, v84, v253
	v_sub_f32_e32 v85, v85, v253
	v_sub_f32_e32 v86, v86, v253
	v_sub_f32_e32 v87, v87, v253
	v_sub_f32_e32 v88, v88, v253
	v_sub_f32_e32 v89, v89, v253
	v_sub_f32_e32 v90, v90, v253
	v_sub_f32_e32 v91, v91, v253
	v_sub_f32_e32 v92, v92, v253
	v_sub_f32_e32 v93, v93, v253
	v_sub_f32_e32 v94, v94, v253
	v_sub_f32_e32 v95, v95, v253
	v_sub_f32_e32 v214, v214, v253
	v_sub_f32_e32 v215, v215, v253
	v_sub_f32_e32 v216, v216, v253
	v_sub_f32_e32 v217, v217, v253
	v_sub_f32_e32 v218, v218, v253
	v_sub_f32_e32 v219, v219, v253
	v_sub_f32_e32 v220, v220, v253
	v_sub_f32_e32 v221, v221, v253
	v_sub_f32_e32 v222, v222, v253
	v_sub_f32_e32 v223, v223, v253
	v_sub_f32_e32 v224, v224, v253
	v_sub_f32_e32 v225, v225, v253
	v_sub_f32_e32 v226, v226, v253
	v_sub_f32_e32 v227, v227, v253
	v_sub_f32_e32 v228, v228, v253
	v_sub_f32_e32 v229, v229, v253
	v_mul_f32_e32 v195, v195, v252
	v_pk_mul_f32 v[78:79], v[78:79], v[252:253] op_sel_hi:[1,0]
	v_pk_mul_f32 v[76:77], v[76:77], v[252:253] op_sel_hi:[1,0]
	v_pk_mul_f32 v[74:75], v[74:75], v[252:253] op_sel_hi:[1,0]
	v_pk_mul_f32 v[72:73], v[72:73], v[252:253] op_sel_hi:[1,0]
	v_pk_mul_f32 v[70:71], v[70:71], v[252:253] op_sel_hi:[1,0]
	v_pk_mul_f32 v[68:69], v[68:69], v[252:253] op_sel_hi:[1,0]
	v_pk_mul_f32 v[66:67], v[66:67], v[252:253] op_sel_hi:[1,0]
	v_pk_mul_f32 v[64:65], v[64:65], v[252:253] op_sel_hi:[1,0]
	v_pk_mul_f32 v[62:63], v[62:63], v[252:253] op_sel_hi:[1,0]
	v_pk_mul_f32 v[60:61], v[60:61], v[252:253] op_sel_hi:[1,0]
	v_pk_mul_f32 v[58:59], v[58:59], v[252:253] op_sel_hi:[1,0]
	v_pk_mul_f32 v[56:57], v[56:57], v[252:253] op_sel_hi:[1,0]
	v_pk_mul_f32 v[54:55], v[54:55], v[252:253] op_sel_hi:[1,0]
	v_pk_mul_f32 v[52:53], v[52:53], v[252:253] op_sel_hi:[1,0]
	v_pk_mul_f32 v[50:51], v[50:51], v[252:253] op_sel_hi:[1,0]
	v_pk_mul_f32 v[48:49], v[48:49], v[252:253] op_sel_hi:[1,0]
	v_pk_mul_f32 v[46:47], v[46:47], v[252:253] op_sel_hi:[1,0]
	v_pk_mul_f32 v[44:45], v[44:45], v[252:253] op_sel_hi:[1,0]
	v_pk_mul_f32 v[42:43], v[42:43], v[252:253] op_sel_hi:[1,0]
	v_pk_mul_f32 v[40:41], v[40:41], v[252:253] op_sel_hi:[1,0]
	v_pk_mul_f32 v[38:39], v[38:39], v[252:253] op_sel_hi:[1,0]
	v_pk_mul_f32 v[36:37], v[36:37], v[252:253] op_sel_hi:[1,0]
	v_pk_mul_f32 v[34:35], v[34:35], v[252:253] op_sel_hi:[1,0]
	v_pk_mul_f32 v[32:33], v[32:33], v[252:253] op_sel_hi:[1,0]
	v_pk_mul_f32 v[30:31], v[30:31], v[252:253] op_sel_hi:[1,0]
	v_pk_mul_f32 v[28:29], v[28:29], v[252:253] op_sel_hi:[1,0]
	v_pk_mul_f32 v[26:27], v[26:27], v[252:253] op_sel_hi:[1,0]
	v_pk_mul_f32 v[24:25], v[24:25], v[252:253] op_sel_hi:[1,0]
	v_pk_mul_f32 v[22:23], v[22:23], v[252:253] op_sel_hi:[1,0]
	v_pk_mul_f32 v[20:21], v[20:21], v[252:253] op_sel_hi:[1,0]
	v_pk_mul_f32 v[18:19], v[18:19], v[252:253] op_sel_hi:[1,0]
	v_pk_mul_f32 v[16:17], v[16:17], v[252:253] op_sel_hi:[1,0]
	s_branch .LBB0_460
.Lrest2:
	v_mov_b32_e32 v214, v162
	v_mov_b32_e32 v216, v163
	v_mov_b32_e32 v218, v164
	v_mov_b32_e32 v220, v166
	v_mov_b32_e32 v222, v168
	v_mov_b32_e32 v224, v170
	v_mov_b32_e32 v226, v172
	v_mov_b32_e32 v228, v174
